# attention prompt items remapped so the workgroups of one XCD take the 32 consecutive query chunks of one (sequence, kv head): each K/V row's three readers share an L2
# speedup vs baseline: 1.0104x; 1.0005x over previous
.LBB0_23:
	s_load_dwordx2 s[2:3], s[0:1], 0x98
	s_mov_b64 s[10:11], 0
	s_waitcnt lgkmcnt(0)
	v_writelane_b32 v252, s2, 22
	s_nop 1
	v_writelane_b32 v252, s3, 23
	s_load_dwordx2 s[2:3], s[0:1], 0x98
	s_waitcnt lgkmcnt(0)
	v_writelane_b32 v252, s2, 24
	s_nop 1
	v_writelane_b32 v252, s3, 25
	s_add_i32 s2, s50, -2
	s_mul_hi_i32 s61, s2, 0x55555556
	s_lshr_b32 s3, s61, 31
	s_add_i32 s61, s61, s3
	s_mul_i32 s3, s61, 3
	s_sub_i32 s34, s2, s3
	s_ashr_i32 s4, s61, 1
	s_and_b32 s2, s61, 1
	s_cmp_eq_u32 s2, 0
	s_cselect_b64 s[6:7], -1, 0
	v_writelane_b32 v252, s6, 26
	s_cmp_eq_u32 s2, 1
	s_cselect_b64 s[2:3], -1, 0
	v_writelane_b32 v252, s7, 27
	v_writelane_b32 v252, s2, 28
	s_ashr_i32 s5, s4, 31
	s_cmp_lt_i32 s34, 1
	v_writelane_b32 v252, s3, 29
	v_writelane_b32 v252, s4, 30
	s_mov_b64 s[2:3], 0
	s_nop 0
	v_writelane_b32 v252, s5, 31
	s_mov_b64 s[4:5], -1
	s_cbranch_scc1 .LBB0_37
	s_cmp_eq_u32 s34, 1
	s_mov_b64 s[2:3], -1
	s_cbranch_scc0 .LBB0_365
	s_load_dwordx2 s[14:15], s[0:1], 0x98
	v_readlane_b32 s2, v252, 22
	v_readlane_b32 s4, v252, 28
	v_readlane_b32 s3, v252, 23
	s_add_u32 s12, s2, 0xb100000
	v_readlane_b32 s5, v252, 29
	s_addc_u32 s13, s3, 0
	s_mov_b64 s[2:3], -1
	s_and_b64 vcc, exec, s[4:5]
	s_cbranch_vccz .LBB0_107
	s_load_dwordx2 s[2:3], s[0:1], 0x98
	v_readlane_b32 s4, v252, 24
	v_readlane_b32 s5, v252, 25
	s_add_u32 s4, s4, 0x23400000
	s_addc_u32 s5, s5, 0
	s_waitcnt lgkmcnt(0)
	s_add_u32 s16, s14, 0x25500000
	s_addc_u32 s17, s15, 0
	s_add_u32 s18, s2, 0x13200000
	s_addc_u32 s19, s3, 0
	s_load_dwordx2 s[20:21], s[0:1], 0x98
	s_load_dwordx2 s[22:23], s[0:1], 0x28
	s_load_dwordx2 s[2:3], s[0:1], 0x30
	s_load_dwordx2 s[8:9], s[0:1], 0x78
	s_mov_b32 s101, s80
	s_cmp_lg_u32 s25, 0x100
	s_cbranch_scc1 .Lat_nomap
	s_and_b32 s101, s80, 7
	s_lshr_b32 s6, s101, 2
	s_lshl_b32 s6, s6, 7
	s_and_b32 s101, s101, 3
	s_or_b32 s101, s101, s6
	s_lshr_b32 s6, s80, 3
	s_lshl_b32 s6, s6, 2
	s_or_b32 s101, s101, s6
.Lat_nomap:
	v_mov_b32 v181, v210
	s_cmpk_lt_i32 s80, 0x1000
	s_waitcnt vmcnt(0)
	v_lshlrev_b32_e32 v0, 4, v181
	v_readfirstlane_b32 s28, v181
	s_cselect_b64 s[6:7], -1, 0
	s_cmpk_gt_i32 s80, 0xfff
	v_lshlrev_b32_e32 v188, 3, v181
	v_and_b32_e32 v0, 0x70, v0
	s_cbranch_scc1 .LBB0_40
	s_sub_i32 s29, 0xfff, s101
	s_and_b64 s[26:27], s[82:83], exec
	s_cselect_b32 s26, s29, s101
	s_bfe_u32 s30, s26, 0x50002
	s_min_u32 s27, s30, 2
	s_and_b32 s29, s26, 3
	s_add_i32 s27, s27, 1
	s_lshl_b32 s26, s26, 4
	s_and_b32 s31, s26, 0xfffff800
	s_sub_i32 s26, s30, s27
	s_lshl_b32 s26, s26, 6
	s_add_i32 s33, s26, s31
	s_lshl_b32 s35, s27, 9
	s_add_i32 s33, s33, 64
	s_lshl_b32 s36, s29, 7
	s_add_u32 s26, s4, s36
	s_addc_u32 s27, s5, 0
	v_mov_b32_e32 v1, v97
	v_lshl_add_u64 v[2:3], s[26:27], 0, v[0:1]
	s_add_u32 s26, s16, s36
	v_mov_b32_e32 v102, v97
	v_mov_b32_e32 v103, v97
	s_addc_u32 s27, s17, 0
	v_mov_b32_e32 v100, v97
	v_mov_b32_e32 v101, v97
	v_mov_b64_e32 v[106:107], v[102:103]
	v_mov_b64_e32 v[110:111], v[102:103]
	v_lshl_add_u64 v[4:5], s[26:27], 0, v[0:1]
	v_cmp_gt_i32_e32 vcc, s35, v181
	v_mov_b64_e32 v[104:105], v[100:101]
	v_mov_b64_e32 v[108:109], v[100:101]
	s_and_saveexec_b64 s[26:27], vcc
	s_cbranch_execz .LBB0_29
	v_ashrrev_i32_e32 v1, 3, v181
	v_add_u32_e32 v6, s33, v1
	v_ashrrev_i32_e32 v7, 31, v6
	v_lshlrev_b64 v[6:7], 9, v[6:7]
	v_lshl_add_u64 v[8:9], v[2:3], 0, v[6:7]
	v_lshl_add_u64 v[6:7], v[4:5], 0, v[6:7]
	global_load_dwordx4 v[104:107], v[8:9], off
	global_load_dwordx4 v[108:111], v[6:7], off

.LBB0_41:
	v_readlane_b32 s26, v252, 30
	v_readlane_b32 s27, v252, 31
	s_lshl_b32 s26, s26, 4
	s_ashr_i32 s27, s26, 31
	s_waitcnt lgkmcnt(0)
	s_add_u32 s20, s20, 0x1b300000
	s_addc_u32 s21, s21, 0
	s_lshl_b64 s[26:27], s[26:27], 2
	v_and_b32_e32 v189, 31, v181
	v_bfe_u32 v190, v181, 5, 1
	s_add_u32 s33, s8, s26
	v_lshlrev_b32_e32 v98, 2, v190
	v_lshrrev_b32_e32 v1, 2, v181
	v_and_b32_e32 v2, 16, v181
	v_lshlrev_b32_e32 v3, 3, v189
	s_addc_u32 s35, s9, s27
	s_bfe_u32 s30, s28, 0x10006
	s_ashr_i32 s36, s28, 7
	s_andn2_b64 vcc, exec, s[6:7]
	v_mul_u32_u24_e32 v99, 0x90, v189
	v_lshlrev_b32_e32 v180, 3, v190
	v_lshlrev_b32_e32 v191, 1, v2
	v_and_b32_e32 v192, 24, v3
	v_and_or_b32 v193, v1, 3, v98
	s_cbranch_vccnz .LBB0_91
	v_and_b32_e32 v1, 0xf8, v188
	s_and_b32 s6, s28, 0xffffff80
	v_lshlrev_b32_e32 v96, 1, v1
	v_mov_b32_e32 v1, v97
	v_add_u32_e32 v196, 0x200, v181
	s_add_i32 s7, s6, 0
	v_lshl_add_u64 v[182:183], s[4:5], 0, v[0:1]
	v_lshl_add_u64 v[184:185], s[16:17], 0, v[0:1]
	v_add_u32_e32 v198, 0x400, v181
	v_ashrrev_i32_e32 v201, 5, v196
	v_mov_b32_e32 v1, s7
	s_movk_i32 s7, 0x210
	v_lshl_or_b32 v2, s30, 5, v189
	v_add_u32_e32 v3, 0, v0
	v_add_u32_e32 v4, 0, v96
	v_add_u32_e32 v194, s67, v96
	v_ashrrev_i32_e32 v202, 5, v198
	v_add_u32_e32 v0, 0x600, v181
	v_mul_lo_u32 v13, v201, s7
	v_ashrrev_i32_e32 v195, 3, v181
	v_ashrrev_i32_e32 v197, 3, v196
	v_ashrrev_i32_e32 v199, 3, v198
	v_ashrrev_i32_e32 v200, 5, v181
	v_ashrrev_i32_e32 v203, 5, v0
	v_mul_u32_u24_e32 v0, 0x210, v2
	v_lshlrev_b32_e32 v5, 4, v190
	s_add_i32 s6, s6, s67
	v_add_u32_e32 v208, v4, v13
	v_add_u32_e32 v209, v194, v13
	v_mul_lo_u32 v13, v202, s7
	v_mad_u32_u24 v1, v2, s7, v1
	v_add_u32_e32 v6, 0, v5
	v_sub_u32_e32 v204, v2, v98
	v_add3_u32 v2, 0, v191, v192
	v_mul_u32_u24_e32 v7, 0xc0, v193
	v_add3_u32 v205, s6, v0, v180
	v_mul_lo_u32 v206, v200, s7
	v_mul_lo_u32 v0, v195, s55
	v_mul_lo_u32 v8, v195, s56
	v_mul_lo_u32 v9, v197, s55
	v_mul_lo_u32 v10, v197, s56
	v_mul_lo_u32 v11, v199, s55
	v_mul_lo_u32 v12, v199, s56
	v_add_u32_e32 v221, v4, v13
	v_add_u32_e32 v222, v194, v13
	v_mul_lo_u32 v13, v203, s7
	v_lshl_add_u64 v[186:187], s[20:21], 0, v[96:97]
	v_add_u32_e32 v207, v4, v206
	v_add_u32_e32 v223, v4, v13
	v_add_u32_e32 v224, v194, v13
	s_sub_i32 s31, 0, s25
	s_sub_i32 s37, 0xfff, s101
	v_add_u32_e32 v225, v3, v0
	v_add_u32_e32 v226, v3, v8
	v_add_u32_e32 v227, v3, v9
	v_add_u32_e32 v228, v3, v10
	v_add_u32_e32 v229, v3, v11
	v_add_u32_e32 v230, v3, v12
	v_add_u32_e32 v231, v1, v5
	v_add_u32_e32 v232, v6, v99
	v_add_u32_e32 v233, v2, v7
	s_mov_b32 s38, s101
	s_branch .LBB0_44

.LBB0_91:
	s_cmp_lg_u32 s25, 0x100
	s_cbranch_scc1 .Lat_orig
	s_and_b64 vcc, exec, s[82:83]
	s_cbranch_vccz .Lat_orig
	s_lshr_b32 s100, s101, 7
	s_lshl_b32 s100, s100, 2
	s_and_b32 s101, s101, 0x7f
	s_cmp_lt_u32 s101, 0x78
	s_cbranch_scc1 .LBB0_106
	s_cmp_lt_u32 s101, 0x7c
	s_cbranch_scc1 .Lat_n1
	s_sub_i32 s101, s101, 0x7c
	s_add_i32 s101, s101, s100
	s_mul_i32 s37, s101, 6
	s_add_i32 s100, s37, 6
	s_mov_b32 s101, 1
	s_branch .Lat_go
